# LDS bank conflicts: SWA transposed-V image XOR-swizzled (bits 3-4 of the in-row offset by column>>3), stores and P.V operand reads 4-way -> 2-way
# speedup vs baseline: 1.0165x; 1.0061x over previous
.LBB0_426:
	v_cndmask_b32_e64 v3, 0, 1, s[92:93]
	v_mov_b64_e32 v[0:1], s[10:11]
	v_readfirstlane_b32 s12, v3
	s_lshl_b32 s9, s12, 2
	s_or_b32 s9, s9, 2
	s_lshl_b32 s12, s12, 9
	s_add_u32 s12, s86, s12
	s_addc_u32 s13, s87, 0
	s_ashr_i32 s26, s8, 7
	s_bfe_u32 s24, s8, 0x60001
	s_ashr_i32 s27, s26, 31
	s_lshl_b64 s[28:29], s[26:27], 13
	s_lshl_b32 s14, s24, 7
	s_or_b32 s28, s28, s14
	s_lshl_b32 s25, s26, 13
	v_lshl_add_u64 v[126:127], s[28:29], 0, v[114:115]
	s_or_b32 s14, s25, s14
	v_or_b32_e32 v4, v126, v112
	s_addk_i32 s14, 0xff80
	s_and_b32 s15, s8, 1
	v_mad_u64_u32 v[4:5], s[28:29], v4, s62, v[0:1]
	v_add_u32_e32 v6, s14, v136
	v_mad_i32_i24 v5, v127, s62, v5
	s_lshl_b32 s94, s15, 9
	v_max_i32_e32 v6, s25, v6
	v_lshl_add_u64 v[4:5], v[4:5], 0, s[94:95]
	v_mad_i64_i32 v[6:7], s[26:27], v6, s62, v[0:1]
	s_lshl_b32 s94, s15, 7
	v_lshl_add_u64 v[6:7], v[6:7], 0, s[94:95]
	v_mov_b32_e32 v123, v2
	v_lshl_add_u64 v[6:7], v[6:7], 0, v[122:123]
	s_mov_b64 s[26:27], 0x1000
	v_lshl_add_u64 v[8:9], v[6:7], 0, s[26:27]
	global_load_dwordx4 v[12:15], v[8:9], off offset:16
	global_load_dwordx4 v[16:19], v[8:9], off offset:32
	s_movk_i32 s28, 0x1000
	v_add_co_u32_e32 v6, vcc, s28, v6
	v_mov_b32_e32 v121, v2
	s_nop 0
	v_addc_co_u32_e32 v7, vcc, 0, v7, vcc
	global_load_dwordx4 v[20:23], v[6:7], off
	global_load_dwordx4 v[24:27], v[116:117], off offset:16
	global_load_dwordx4 v[28:31], v[116:117], off
	global_load_dwordx4 v[32:35], v[8:9], off offset:48
	v_add_u32_e32 v6, s14, v137
	v_max_i32_e32 v10, s25, v6
	v_mad_i64_i32 v[6:7], s[26:27], v10, s62, v[0:1]
	v_mov_b32_e32 v125, v2
	v_or_b32_e32 v10, 1, v10
	v_lshl_add_u64 v[4:5], v[4:5], 0, v[120:121]
	v_lshl_add_u64 v[6:7], v[6:7], 0, s[94:95]
	v_mad_i64_i32 v[0:1], s[26:27], v10, s62, v[0:1]
	global_load_dwordx4 v[96:99], v[4:5], off offset:3072
	global_load_dwordx4 v[100:103], v[4:5], off offset:3136
	v_lshl_add_u64 v[4:5], v[6:7], 0, v[124:125]
	s_mov_b64 s[16:17], 0x1100
	v_lshl_add_u64 v[0:1], v[0:1], 0, s[94:95]
	v_lshl_add_u64 v[48:49], v[4:5], 0, s[16:17]
	v_add_co_u32_e32 v4, vcc, s28, v4
	v_lshl_add_u64 v[0:1], v[0:1], 0, v[124:125]
	s_nop 0
	v_addc_co_u32_e32 v5, vcc, 0, v5, vcc
	v_lshl_add_u64 v[50:51], v[0:1], 0, s[16:17]
	v_add_co_u32_e32 v0, vcc, s28, v0
	s_mov_b32 s14, 0xffff0000
	s_nop 0
	v_addc_co_u32_e32 v1, vcc, 0, v1, vcc
	global_load_dwordx4 v[4:7], v[4:5], off offset:256
	s_nop 0
	global_load_dwordx4 v[8:11], v[0:1], off offset:256
	v_readlane_b32 s16, v253, 11
	v_readlane_b32 s17, v253, 12
	v_mov_b32_e32 v129, v2
	s_mov_b64 s[70:71], 0
	s_movk_i32 s94, 0x210
	s_mov_b32 s18, 0x41800000
	s_mov_b32 s19, 0x41880000
	s_mov_b32 s20, 0x41900000
	s_mov_b32 s21, 0x41980000
	s_mov_b32 s22, 0x42000000
	s_waitcnt vmcnt(9)
	v_and_b32_e32 v53, 0xffff0000, v13
	v_and_b32_e32 v52, 0xffff0000, v12
	v_and_b32_e32 v57, 0xffff0000, v15
	v_and_b32_e32 v56, 0xffff0000, v14
	v_lshlrev_b32_e32 v1, 16, v13
	v_lshlrev_b32_e32 v0, 16, v12
	v_lshlrev_b32_e32 v55, 16, v15
	v_lshlrev_b32_e32 v54, 16, v14
	s_waitcnt vmcnt(8)
	v_and_b32_e32 v59, 0xffff0000, v16
	v_and_b32_e32 v61, 0xffff0000, v17
	v_pk_mul_f32 v[12:13], v[52:53], v[52:53]
	v_pk_mul_f32 v[14:15], v[56:57], v[56:57]
	v_lshlrev_b32_e32 v58, 16, v16
	v_lshlrev_b32_e32 v60, 16, v17
	v_lshlrev_b32_e32 v62, 16, v18
	v_and_b32_e32 v63, 0xffff0000, v18
	v_mul_f32_e32 v16, v59, v59
	v_mul_f32_e32 v18, v61, v61
	v_pk_fma_f32 v[12:13], v[0:1], v[0:1], v[12:13]
	v_pk_fma_f32 v[14:15], v[54:55], v[54:55], v[14:15]
	v_lshlrev_b32_e32 v64, 16, v19
	v_and_b32_e32 v65, 0xffff0000, v19
	v_pk_fma_f32 v[66:67], v[58:59], v[58:59], v[16:17] op_sel_hi:[1,1,0]
	v_pk_fma_f32 v[68:69], v[60:61], v[60:61], v[18:19] op_sel_hi:[1,1,0]
	v_pk_add_f32 v[72:73], v[12:13], v[12:13] op_sel:[0,1] op_sel_hi:[1,0]
	v_pk_add_f32 v[74:75], v[14:15], v[14:15] op_sel:[0,1] op_sel_hi:[1,0]
	global_load_dwordx4 v[12:15], v[116:117], off offset:48
	global_load_dwordx4 v[16:19], v[116:117], off offset:32
	v_mul_f32_e32 v36, v63, v63
	s_waitcnt vmcnt(9)
	v_and_b32_e32 v79, 0xffff0000, v23
	v_and_b32_e32 v81, 0xffff0000, v22
	v_pk_fma_f32 v[70:71], v[62:63], v[62:63], v[36:37] op_sel_hi:[1,1,0]
	v_lshlrev_b32_e32 v78, 16, v23
	v_lshlrev_b32_e32 v80, 16, v22
	v_mov_b32_e32 v36, v81
	v_mov_b32_e32 v37, v79
	v_mov_b32_e32 v22, v80
	v_mov_b32_e32 v23, v78
	v_pk_mul_f32 v[36:37], v[36:37], v[36:37]
	v_mul_f32_e32 v38, v65, v65
	v_pk_fma_f32 v[22:23], v[22:23], v[22:23], v[36:37]
	v_pk_fma_f32 v[76:77], v[64:65], v[64:65], v[38:39] op_sel_hi:[1,1,0]
	v_pk_add_f32 v[82:83], v[22:23], v[22:23] op_sel:[0,1] op_sel_hi:[1,0]
	v_lshlrev_b32_e32 v84, 16, v21
	v_and_b32_e32 v85, 0xffff0000, v21
	v_lshlrev_b32_e32 v86, 16, v20
	v_and_b32_e32 v87, 0xffff0000, v20
	global_load_dwordx4 v[20:23], v[116:117], off offset:80
	global_load_dwordx4 v[36:39], v[116:117], off offset:64
	v_mov_b32_e32 v42, v87
	v_mov_b32_e32 v43, v85
	v_mov_b32_e32 v40, v86
	v_mov_b32_e32 v41, v84
	v_pk_mul_f32 v[42:43], v[42:43], v[42:43]
	s_waitcnt vmcnt(8)
	v_lshlrev_b32_e32 v90, 16, v35
	v_pk_fma_f32 v[40:41], v[40:41], v[40:41], v[42:43]
	v_and_b32_e32 v91, 0xffff0000, v35
	v_pk_add_f32 v[88:89], v[40:41], v[40:41] op_sel:[0,1] op_sel_hi:[1,0]
	global_load_dwordx4 v[40:43], v[116:117], off offset:112
	global_load_dwordx4 v[44:47], v[116:117], off offset:96
	v_pk_mul_f32 v[92:93], v[90:91], v[90:91]
	s_nop 0
	v_mov_b32_e32 v71, v92
	v_mov_b32_e32 v77, v93
	v_pk_add_f32 v[70:71], v[70:71], v[76:77]
	v_lshlrev_b32_e32 v76, 16, v34
	v_and_b32_e32 v77, 0xffff0000, v34
	v_pk_mul_f32 v[34:35], v[76:77], v[76:77]
	s_nop 0
	v_mov_b32_e32 v67, v34
	v_mov_b32_e32 v69, v35
	v_pk_add_f32 v[34:35], v[66:67], v[68:69]
	v_lshlrev_b32_e32 v66, 16, v33
	v_pk_add_f32 v[34:35], v[34:35], v[70:71]
	v_and_b32_e32 v67, 0xffff0000, v33
	v_lshlrev_b32_e32 v70, 16, v32
	v_and_b32_e32 v71, 0xffff0000, v32
	v_pk_mul_f32 v[68:69], v[66:67], v[66:67]
	v_pk_mul_f32 v[32:33], v[70:71], v[70:71]
	v_mov_b32_e32 v73, v68
	v_mov_b32_e32 v75, v69
	v_mov_b32_e32 v89, v32
	v_mov_b32_e32 v83, v33
	v_pk_add_f32 v[68:69], v[72:73], v[74:75]
	v_pk_add_f32 v[32:33], v[88:89], v[82:83]
	s_nop 0
	v_pk_add_f32 v[32:33], v[32:33], v[68:69]
	v_mov_b32_e32 v68, v0
	v_pk_add_f32 v[32:33], v[32:33], v[34:35]
	v_mov_b32_e32 v69, v52
	v_add_f32_e32 v72, v32, v33
	global_load_dwordx4 v[32:35], v[48:49], off offset:16
	s_nop 0
	global_load_dwordx4 v[48:51], v[50:51], off offset:16
	ds_bpermute_b32 v73, v138, v72
	v_mov_b32_e32 v52, v1
	s_waitcnt lgkmcnt(0)
	v_add_f32_e32 v0, v72, v73
	v_fmamk_f32 v0, v0, 0x3c800000, v209
	v_mul_f32_e32 v1, 0x4b800000, v0
	v_cmp_gt_f32_e32 vcc, s68, v0
	s_nop 1
	v_cndmask_b32_e32 v0, v0, v1, vcc
	v_rsq_f32_e32 v72, v0
	v_mov_b32_e32 v0, v54
	v_mov_b32_e32 v1, v56
	v_mov_b32_e32 v56, v55
	v_mul_f32_e32 v54, 0x45800000, v72
	v_cndmask_b32_e32 v54, v72, v54, vcc
	v_pk_mul_f32 v[72:73], v[54:55], v[86:87] op_sel_hi:[0,1]
	v_pk_mul_f32 v[28:29], v[28:29], v[72:73]
	v_pk_mul_f32 v[72:73], v[54:55], v[84:85] op_sel_hi:[0,1]
	v_pk_mul_f32 v[30:31], v[30:31], v[72:73]
	v_cvt_pk_bf16_f32 v28, v28, v29
	v_cvt_pk_bf16_f32 v29, v30, v31
	v_pk_mul_f32 v[30:31], v[54:55], v[80:81] op_sel_hi:[0,1]
	v_pk_mul_f32 v[24:25], v[24:25], v[30:31]
	v_pk_mul_f32 v[0:1], v[54:55], v[0:1] op_sel_hi:[0,1]
	v_cvt_pk_bf16_f32 v30, v24, v25
	v_pk_mul_f32 v[24:25], v[54:55], v[78:79] op_sel_hi:[0,1]
	v_pk_mul_f32 v[24:25], v[26:27], v[24:25]
	s_waitcnt vmcnt(7)
	v_pk_mul_f32 v[0:1], v[12:13], v[0:1]
	v_cvt_pk_bf16_f32 v31, v24, v25
	v_pk_mul_f32 v[24:25], v[54:55], v[68:69] op_sel_hi:[0,1]
	s_waitcnt vmcnt(6)
	v_pk_mul_f32 v[16:17], v[16:17], v[24:25]
	v_pk_mul_f32 v[24:25], v[54:55], v[52:53] op_sel_hi:[0,1]
	v_pk_mul_f32 v[18:19], v[18:19], v[24:25]
	v_cvt_pk_bf16_f32 v16, v16, v17
	v_cvt_pk_bf16_f32 v17, v18, v19
	v_cvt_pk_bf16_f32 v18, v0, v1
	v_pk_mul_f32 v[0:1], v[54:55], v[56:57] op_sel_hi:[0,1]
	v_pk_mul_f32 v[0:1], v[14:15], v[0:1]
	ds_write_b128 v139, v[28:31]
	v_cvt_pk_bf16_f32 v19, v0, v1
	v_pk_mul_f32 v[0:1], v[54:55], v[58:59] op_sel_hi:[0,1]
	s_waitcnt vmcnt(4)
	v_pk_mul_f32 v[0:1], v[36:37], v[0:1]
	ds_write_b128 v139, v[16:19] offset:16
	v_cvt_pk_bf16_f32 v12, v0, v1
	v_pk_mul_f32 v[0:1], v[54:55], v[60:61] op_sel_hi:[0,1]
	v_pk_mul_f32 v[0:1], v[38:39], v[0:1]
	s_nop 0
	v_cvt_pk_bf16_f32 v13, v0, v1
	v_pk_mul_f32 v[0:1], v[54:55], v[62:63] op_sel_hi:[0,1]
	v_pk_mul_f32 v[0:1], v[20:21], v[0:1]
	s_nop 0
	v_cvt_pk_bf16_f32 v14, v0, v1
	v_pk_mul_f32 v[0:1], v[54:55], v[64:65] op_sel_hi:[0,1]
	v_pk_mul_f32 v[0:1], v[22:23], v[0:1]
	s_nop 0
	v_cvt_pk_bf16_f32 v15, v0, v1
	v_pk_mul_f32 v[0:1], v[54:55], v[70:71] op_sel_hi:[0,1]
	s_waitcnt vmcnt(2)
	v_pk_mul_f32 v[0:1], v[44:45], v[0:1]
	ds_write_b128 v139, v[12:15] offset:32
	v_cvt_pk_bf16_f32 v12, v0, v1
	v_pk_mul_f32 v[0:1], v[54:55], v[66:67] op_sel_hi:[0,1]
	v_pk_mul_f32 v[0:1], v[46:47], v[0:1]
	s_nop 0
	v_cvt_pk_bf16_f32 v13, v0, v1
	v_pk_mul_f32 v[0:1], v[54:55], v[76:77] op_sel_hi:[0,1]
	v_pk_mul_f32 v[0:1], v[40:41], v[0:1]
	s_nop 0
	v_cvt_pk_bf16_f32 v14, v0, v1
	v_pk_mul_f32 v[0:1], v[54:55], v[90:91] op_sel_hi:[0,1]
	v_pk_mul_f32 v[0:1], v[42:43], v[0:1]
	s_nop 0
	v_cvt_pk_bf16_f32 v15, v0, v1
	v_and_b32_e32 v0, 0xffff, v4
	v_lshrrev_b32_e32 v1, 16, v4
	v_lshl_or_b32 v0, v8, 16, v0
	v_and_or_b32 v1, v8, s14, v1
	v_and_b32_e32 v28, 1, v208
	v_lshlrev_b32_e32 v28, 4, v28
	v_xor_b32_e32 v28, v145, v28
	v_xor_b32_e32 v29, 8, v28
	v_add_u32_e32 v4, 0x9000, v28
	ds_write_b128 v139, v[12:15] offset:48
	ds_write2_b32 v4, v0, v1 offset1:132
	v_and_b32_e32 v0, 0xffff, v5
	v_lshrrev_b32_e32 v1, 16, v5
	v_lshl_or_b32 v0, v9, 16, v0
	v_and_or_b32 v1, v9, s14, v1
	v_add_u32_e32 v4, 0x9400, v28
	ds_write2_b32 v4, v0, v1 offset0:8 offset1:140
	v_and_b32_e32 v0, 0xffff, v6
	v_lshrrev_b32_e32 v1, 16, v6
	v_lshl_or_b32 v0, v10, 16, v0
	v_and_or_b32 v1, v10, s14, v1
	v_add_u32_e32 v4, 0x9800, v28
	ds_write2_b32 v4, v0, v1 offset0:16 offset1:148
	v_and_b32_e32 v0, 0xffff, v7
	v_lshrrev_b32_e32 v1, 16, v7
	v_lshl_or_b32 v0, v11, 16, v0
	v_and_or_b32 v1, v11, s14, v1
	v_add_u32_e32 v4, 0x9c00, v28
	ds_write2_b32 v4, v0, v1 offset0:24 offset1:156
	s_waitcnt vmcnt(1)
	v_and_b32_e32 v0, 0xffff, v32
	v_lshrrev_b32_e32 v1, 16, v32
	s_waitcnt vmcnt(0)
	v_lshl_or_b32 v0, v48, 16, v0
	v_and_or_b32 v1, v48, s14, v1
	v_add_u32_e32 v4, 0xa000, v29
	ds_write2_b32 v4, v0, v1 offset0:32 offset1:164
	v_and_b32_e32 v0, 0xffff, v33
	v_lshrrev_b32_e32 v1, 16, v33
	v_lshl_or_b32 v0, v49, 16, v0
	v_and_or_b32 v1, v49, s14, v1
	v_add_u32_e32 v4, 0xa400, v29
	ds_write2_b32 v4, v0, v1 offset0:40 offset1:172
	v_and_b32_e32 v0, 0xffff, v34
	v_lshrrev_b32_e32 v1, 16, v34
	v_lshl_or_b32 v0, v50, 16, v0
	v_and_or_b32 v1, v50, s14, v1
	v_add_u32_e32 v4, 0xa800, v29
	ds_write2_b32 v4, v0, v1 offset0:48 offset1:180
	v_and_b32_e32 v0, 0xffff, v35
	v_lshrrev_b32_e32 v1, 16, v35
	v_lshl_or_b32 v0, v51, 16, v0
	v_and_or_b32 v1, v51, s14, v1
	v_add_u32_e32 v4, 0xac00, v29
	ds_write2_b32 v4, v0, v1 offset0:56 offset1:188
	s_waitcnt lgkmcnt(0)
	s_barrier
	global_load_dwordx4 v[4:7], v[118:119], off
	global_load_dwordx4 v[8:11], v[118:119], off offset:16
	global_load_dwordx4 v[12:15], v[118:119], off offset:128
	global_load_dwordx4 v[16:19], v[118:119], off offset:144
	s_lshl_b32 s14, s15, 4
	v_mov_b32_e32 v0, s14
	global_load_dwordx4 v[20:23], v0, s[6:7]
	v_lshlrev_b32_e32 v0, 8, v3
	v_or_b32_e32 v128, 64, v0
	v_add_u32_e32 v0, v140, v144
	ds_read_b128 v[24:27], v0
	ds_read_b128 v[28:31], v0 offset:64
	ds_read_b128 v[32:35], v146
	ds_read_b128 v[36:39], v146 offset:64
	ds_read_b128 v[40:43], v147
	ds_read_b128 v[44:47], v147 offset:64
	ds_read_b128 v[48:51], v148
	ds_read_b128 v[52:55], v148 offset:64
	ds_read_b128 v[56:59], v149
	ds_read_b128 v[60:63], v149 offset:64
	ds_read_b128 v[64:67], v150
	ds_read_b128 v[68:71], v150 offset:64
	ds_read_b128 v[72:75], v151
	ds_read_b128 v[76:79], v151 offset:64
	ds_read_b128 v[80:83], v152
	ds_read_b128 v[84:87], v152 offset:64
	ds_read_b128 v[88:91], v153
	ds_read_b128 v[92:95], v153 offset:64
	s_lshl_b32 s15, s15, 2
	s_cmp_lg_u32 s24, 0
	s_cselect_b64 s[40:41], -1, 0
	s_or_b64 s[78:79], s[40:41], s[16:17]
	v_readlane_b32 s16, v253, 13
	v_readlane_b32 s17, v253, 14
	s_or_b64 s[24:25], s[40:41], s[16:17]
	v_readlane_b32 s16, v253, 15
	v_readlane_b32 s17, v253, 16
	s_or_b64 s[26:27], s[40:41], s[16:17]
	v_readlane_b32 s16, v253, 17
	v_readlane_b32 s17, v253, 18
	s_or_b64 s[28:29], s[40:41], s[16:17]
	v_readlane_b32 s16, v253, 19
	v_readlane_b32 s17, v253, 20
	s_or_b64 s[30:31], s[40:41], s[16:17]
	v_readlane_b32 s16, v253, 21
	v_readlane_b32 s17, v253, 22
	s_or_b64 s[34:35], s[40:41], s[16:17]
	v_readlane_b32 s16, v253, 23
	v_readlane_b32 s17, v253, 24
	s_or_b64 s[36:37], s[40:41], s[16:17]
	v_readlane_b32 s16, v253, 25
	v_readlane_b32 s17, v253, 26
	s_or_b64 s[38:39], s[40:41], s[16:17]
	v_readlane_b32 s16, v253, 27
	v_readlane_b32 s17, v253, 28
	s_mov_b32 s14, 0
	s_or_b64 s[84:85], s[40:41], s[16:17]
	s_mov_b32 s16, 0x42800000
	s_mov_b32 s17, 0x40400000
	s_branch .LBB0_429

.LBB0_428:
	s_waitcnt vmcnt(3)
	v_lshlrev_b32_e32 v186, 16, v104
	v_and_b32_e32 v187, 0xffff0000, v104
	v_lshlrev_b32_e32 v182, 16, v105
	v_and_b32_e32 v183, 0xffff0000, v105
	v_pk_mul_f32 v[104:105], v[186:187], v[186:187]
	v_pk_mul_f32 v[184:185], v[182:183], v[182:183]
	v_add_f32_e32 v1, v104, v105
	v_lshlrev_b32_e32 v180, 16, v106
	v_and_b32_e32 v181, 0xffff0000, v106
	v_add_f32_e32 v1, v184, v1
	v_lshlrev_b32_e32 v176, 16, v107
	v_and_b32_e32 v177, 0xffff0000, v107
	v_pk_mul_f32 v[106:107], v[180:181], v[180:181]
	v_add_f32_e32 v1, v185, v1
	v_add_f32_e32 v1, v106, v1
	v_pk_mul_f32 v[178:179], v[176:177], v[176:177]
	v_add_f32_e32 v1, v107, v1
	s_waitcnt vmcnt(2)
	v_lshlrev_b32_e32 v174, 16, v108
	v_and_b32_e32 v175, 0xffff0000, v108
	v_add_f32_e32 v1, v178, v1
	v_lshlrev_b32_e32 v170, 16, v109
	v_and_b32_e32 v171, 0xffff0000, v109
	v_pk_mul_f32 v[108:109], v[174:175], v[174:175]
	v_add_f32_e32 v1, v179, v1
	v_add_f32_e32 v1, v108, v1
	v_pk_mul_f32 v[172:173], v[170:171], v[170:171]
	v_add_f32_e32 v1, v109, v1
	v_lshlrev_b32_e32 v160, 16, v110
	v_and_b32_e32 v161, 0xffff0000, v110
	v_add_f32_e32 v1, v172, v1
	v_lshlrev_b32_e32 v154, 16, v111
	v_and_b32_e32 v155, 0xffff0000, v111
	v_pk_mul_f32 v[110:111], v[160:161], v[160:161]
	v_add_f32_e32 v1, v173, v1
	v_add_f32_e32 v1, v110, v1
	v_pk_mul_f32 v[158:159], v[154:155], v[154:155]
	v_add_f32_e32 v1, v111, v1
	v_add_f32_e32 v1, v158, v1
	v_add_f32_e32 v1, v159, v1
	ds_bpermute_b32 v104, v141, v1
	v_lshlrev_b32_e32 v3, 2, v3
	v_sub_u32_e32 v3, v0, v3
	s_mov_b32 s17, 0x40400000
	s_mov_b32 s18, 0x41800000
	s_waitcnt lgkmcnt(0)
	v_add_f32_e32 v1, v1, v104
	ds_bpermute_b32 v104, v142, v1
	s_mov_b32 s19, 0x41880000
	s_mov_b32 s20, 0x41900000
	s_mov_b32 s21, 0x41980000
	s_mov_b32 s22, 0x42000000
	s_waitcnt lgkmcnt(0)
	v_add_f32_e32 v1, v1, v104
	v_fmamk_f32 v1, v1, 0x3c800000, v209
	v_cmp_gt_f32_e32 vcc, s68, v1
	v_mul_f32_e32 v104, 0x4b800000, v1
	s_mov_b32 s16, 0x42800000
	v_cndmask_b32_e32 v1, v1, v104, vcc
	v_rsq_f32_e32 v1, v1
	s_movk_i32 s94, 0x210
	v_lshlrev_b64 v[132:133], 11, v[132:133]
	v_lshl_add_u64 v[132:133], s[86:87], 0, v[132:133]
	v_mul_f32_e32 v104, 0x45800000, v1
	v_cndmask_b32_e32 v1, v1, v104, vcc
	v_mul_f32_e32 v158, 0x3e38aa3b, v1
	v_pk_mul_f32 v[104:105], v[158:159], v[186:187] op_sel_hi:[0,1]
	v_pk_mul_f32 v[106:107], v[158:159], v[182:183] op_sel_hi:[0,1]
	v_pk_mul_f32 v[104:105], v[4:5], v[104:105]
	v_pk_mul_f32 v[106:107], v[6:7], v[106:107]
	v_cvt_pk_bf16_f32 v104, v104, v105
	v_cvt_pk_bf16_f32 v105, v106, v107
	v_pk_mul_f32 v[106:107], v[158:159], v[180:181] op_sel_hi:[0,1]
	v_pk_mul_f32 v[108:109], v[158:159], v[176:177] op_sel_hi:[0,1]
	v_pk_mul_f32 v[106:107], v[8:9], v[106:107]
	v_pk_mul_f32 v[108:109], v[10:11], v[108:109]
	v_cvt_pk_bf16_f32 v106, v106, v107
	v_cvt_pk_bf16_f32 v107, v108, v109
	v_pk_mul_f32 v[108:109], v[158:159], v[174:175] op_sel_hi:[0,1]
	v_pk_mul_f32 v[110:111], v[158:159], v[170:171] op_sel_hi:[0,1]
	v_cvt_f32_u32_e32 v1, s9
	v_pk_mul_f32 v[108:109], v[12:13], v[108:109]
	v_pk_mul_f32 v[110:111], v[14:15], v[110:111]
	v_mfma_f32_16x16x32_bf16 v[170:173], v[24:27], v[104:107], 0
	v_cvt_pk_bf16_f32 v108, v108, v109
	v_cvt_pk_bf16_f32 v109, v110, v111
	v_pk_mul_f32 v[110:111], v[158:159], v[160:161] op_sel_hi:[0,1]
	v_mfma_f32_16x16x32_bf16 v[174:177], v[32:35], v[104:107], 0
	v_mul_f32_e64 v154, v158, v154
	v_mul_f32_e64 v155, v158, v155
	v_pk_mul_f32 v[110:111], v[16:17], v[110:111]
	v_pk_mul_f32 v[154:155], v[18:19], v[154:155]
	v_mfma_f32_16x16x32_bf16 v[178:181], v[40:43], v[104:107], 0
	v_cvt_pk_bf16_f32 v110, v110, v111
	v_cvt_pk_bf16_f32 v111, v154, v155
	v_cmp_lt_f32_e32 vcc, s57, v1
	v_mfma_f32_16x16x32_bf16 v[182:185], v[48:51], v[104:107], 0
	s_and_b64 s[40:41], vcc, exec
	s_cselect_b32 s40, 0xffffffc0, 0
	s_cmp_eq_u32 s42, 1
	v_mfma_f32_16x16x32_bf16 v[186:189], v[56:59], v[104:107], 0
	v_lshl_add_u64 v[132:133], v[134:135], 1, v[132:133]
	v_lshl_add_u64 v[128:129], v[128:129], 0, s[76:77]
	v_mfma_f32_16x16x32_bf16 v[190:193], v[64:67], v[104:107], 0
	v_mfma_f32_16x16x32_bf16 v[194:197], v[72:75], v[104:107], 0
	v_mfma_f32_16x16x32_bf16 v[198:201], v[80:83], v[104:107], 0
	v_mfma_f32_16x16x32_bf16 v[104:107], v[88:91], v[104:107], 0
	v_mfma_f32_16x16x32_bf16 v[170:173], v[28:31], v[108:111], v[170:173]
	v_mfma_f32_16x16x32_bf16 v[174:177], v[36:39], v[108:111], v[174:177]
	v_mfma_f32_16x16x32_bf16 v[178:181], v[44:47], v[108:111], v[178:181]
	v_mfma_f32_16x16x32_bf16 v[182:185], v[52:55], v[108:111], v[182:185]
	v_mfma_f32_16x16x32_bf16 v[186:189], v[60:63], v[108:111], v[186:189]
	v_mfma_f32_16x16x32_bf16 v[190:193], v[68:71], v[108:111], v[190:193]
	v_mfma_f32_16x16x32_bf16 v[194:197], v[76:79], v[108:111], v[194:197]
	v_mfma_f32_16x16x32_bf16 v[198:201], v[84:87], v[108:111], v[198:201]
	v_mfma_f32_16x16x32_bf16 v[104:107], v[92:95], v[108:111], v[104:107]
	v_cndmask_b32_e32 v108, 0, v215, vcc
	v_sub_f32_e32 v1, v108, v1
	v_exp_f32_e32 v1, v1
	s_cselect_b64 vcc, -1, 0
	v_add_u32_e32 v110, 0x80, v3
	v_cvt_f32_i32_e32 v157, v110
	v_ldexp_f32 v109, v1, s40
	v_cndmask_b32_e32 v1, v23, v21, vcc
	v_cmp_gt_i32_e32 vcc, 0, v3
	s_and_b64 s[46:47], s[78:79], vcc
	v_cmp_gt_i32_e32 vcc, 1, v3
	s_and_b64 s[48:49], s[78:79], vcc
	v_cmp_gt_i32_e32 vcc, 2, v3
	s_and_b64 s[50:51], s[78:79], vcc
	v_cmp_gt_i32_e32 vcc, 3, v3
	s_and_b64 s[52:53], s[78:79], vcc
	v_cmp_lt_i32_e32 vcc, -1, v3
	v_mul_f32_e32 v108, 0x3fb8aa3b, v109
	s_and_b64 s[44:45], s[84:85], vcc
	v_cmp_lt_i32_e32 vcc, 0, v3
	s_and_b64 s[42:43], s[84:85], vcc
	v_cmp_lt_i32_e32 vcc, 1, v3
	v_pk_mul_f32 v[110:111], v[108:109], v[156:157] op_sel_hi:[0,1]
	s_and_b64 s[40:41], s[84:85], vcc
	v_cmp_lt_i32_e32 vcc, 2, v3
	v_fma_f32 v3, v108, 0, -v111
	v_fma_f32 v109, v109, s65, -v111
	v_add_f32_e32 v3, v3, v170
	v_add_f32_e32 v109, v109, v171
	v_fma_f32 v123, v108, 2.0, -v111
	v_fma_f32 v125, v108, s17, -v111
	v_mul_f32_e32 v121, 0x3fb8aa3b, v1
	v_cndmask_b32_e64 v3, v216, v3, s[46:47]
	v_cndmask_b32_e64 v109, v216, v109, s[48:49]
	v_add_f32_e32 v123, v123, v172
	v_add_f32_e32 v125, v125, v173
	v_fma_f32 v154, v108, s18, -v111
	v_fma_f32 v155, v108, s19, -v111
	v_max3_f32 v121, v121, v3, v109
	v_cndmask_b32_e64 v123, v216, v123, s[50:51]
	v_cndmask_b32_e64 v125, v216, v125, s[52:53]
	v_add_f32_e32 v154, v154, v174
	v_add_f32_e32 v155, v155, v175
	v_fma_f32 v157, v108, s20, -v111
	v_fma_f32 v158, v108, s21, -v111
	v_max3_f32 v121, v121, v123, v125
	v_cndmask_b32_e64 v154, v216, v154, s[24:25]
	v_cndmask_b32_e64 v155, v216, v155, s[24:25]
	v_add_f32_e32 v157, v157, v176
	v_add_f32_e32 v158, v158, v177
	v_fma_f32 v159, v108, s22, -v111
	v_fma_f32 v160, v108, s0, -v111
	v_max3_f32 v121, v121, v154, v155
	v_cndmask_b32_e64 v157, v216, v157, s[24:25]
	v_cndmask_b32_e64 v158, v216, v158, s[24:25]
	v_add_f32_e32 v159, v159, v178
	v_add_f32_e32 v160, v160, v179
	v_fma_f32 v161, v108, s33, -v111
	v_fma_f32 v170, v108, s61, -v111
	v_max3_f32 v121, v121, v157, v158
	v_cndmask_b32_e64 v159, v216, v159, s[26:27]
	v_cndmask_b32_e64 v160, v216, v160, s[26:27]
	v_add_f32_e32 v161, v161, v180
	v_add_f32_e32 v170, v170, v181
	v_fma_f32 v171, v108, s4, -v111
	v_fma_f32 v172, v108, s81, -v111
	v_max3_f32 v121, v121, v159, v160
	v_cndmask_b32_e64 v161, v216, v161, s[26:27]
	v_cndmask_b32_e64 v170, v216, v170, s[26:27]
	v_add_f32_e32 v171, v171, v182
	v_add_f32_e32 v172, v172, v183
	v_fma_f32 v173, v108, s69, -v111
	v_fma_f32 v174, v108, s59, -v111
	v_max3_f32 v121, v121, v161, v170
	v_cndmask_b32_e64 v171, v216, v171, s[28:29]
	v_cndmask_b32_e64 v172, v216, v172, s[28:29]
	v_add_f32_e32 v173, v173, v184
	v_add_f32_e32 v174, v174, v185
	v_fma_f32 v175, v108, s16, -v111
	v_fma_f32 v176, v108, s58, -v111
	v_max3_f32 v121, v121, v171, v172
	v_cndmask_b32_e64 v173, v216, v173, s[28:29]
	v_cndmask_b32_e64 v174, v216, v174, s[28:29]
	v_add_f32_e32 v175, v175, v186
	v_add_f32_e32 v176, v176, v187
	v_fma_f32 v177, v108, s64, -v111
	v_fma_f32 v178, v108, s3, -v111
	v_max3_f32 v121, v121, v173, v174
	v_cndmask_b32_e64 v175, v216, v175, s[30:31]
	v_cndmask_b32_e64 v176, v216, v176, s[30:31]
	v_add_f32_e32 v177, v177, v188
	v_add_f32_e32 v178, v178, v189
	v_fma_f32 v179, v108, s2, -v111
	v_fma_f32 v180, v108, s63, -v111
	v_max3_f32 v121, v121, v175, v176
	v_cndmask_b32_e64 v177, v216, v177, s[30:31]
	v_cndmask_b32_e64 v178, v216, v178, s[30:31]
	v_add_f32_e32 v179, v179, v190
	v_add_f32_e32 v180, v180, v191
	v_fma_f32 v181, v108, s82, -v111
	v_fma_f32 v182, v108, s83, -v111
	v_max3_f32 v121, v121, v177, v178
	v_cndmask_b32_e64 v179, v216, v179, s[34:35]
	v_cndmask_b32_e64 v180, v216, v180, s[34:35]
	v_add_f32_e32 v181, v181, v192
	v_add_f32_e32 v182, v182, v193
	v_fma_f32 v183, v108, s80, -v111
	v_fma_f32 v184, v108, s90, -v111
	v_max3_f32 v121, v121, v179, v180
	v_cndmask_b32_e64 v181, v216, v181, s[34:35]
	v_cndmask_b32_e64 v182, v216, v182, s[34:35]
	v_add_f32_e32 v183, v183, v194
	v_add_f32_e32 v184, v184, v195
	v_fma_f32 v185, v108, s91, -v111
	v_fma_f32 v186, v108, s88, -v111
	v_max3_f32 v121, v121, v181, v182
	v_cndmask_b32_e64 v183, v216, v183, s[36:37]
	v_cndmask_b32_e64 v184, v216, v184, s[36:37]
	v_add_f32_e32 v185, v185, v196
	v_add_f32_e32 v186, v186, v197
	v_fma_f32 v187, v108, s89, -v111
	v_fma_f32 v188, v108, s75, -v111
	v_max3_f32 v121, v121, v183, v184
	v_cndmask_b32_e64 v185, v216, v185, s[36:37]
	v_cndmask_b32_e64 v186, v216, v186, s[36:37]
	v_add_f32_e32 v187, v187, v198
	v_add_f32_e32 v188, v188, v199
	v_fma_f32 v189, v108, s96, -v111
	v_fma_f32 v190, v108, s97, -v111
	v_fma_f32 v191, v108, s5, -v111
	v_max3_f32 v121, v121, v185, v186
	v_cndmask_b32_e64 v187, v216, v187, s[38:39]
	v_cndmask_b32_e64 v188, v216, v188, s[38:39]
	v_add_f32_e32 v189, v189, v200
	v_add_f32_e32 v190, v190, v201
	v_add_f32_e32 v104, v191, v104
	v_fma_f32 v191, v108, s60, -v111
	v_fma_f32 v108, v108, s66, -v111
	v_max3_f32 v121, v121, v187, v188
	v_cndmask_b32_e64 v189, v216, v189, s[38:39]
	v_cndmask_b32_e64 v190, v216, v190, s[38:39]
	v_add_f32_e32 v105, v191, v105
	v_add_f32_e32 v106, v108, v106
	v_sub_f32_e32 v108, v110, v111
	s_and_b64 vcc, s[84:85], vcc
	v_max3_f32 v121, v121, v189, v190
	v_cndmask_b32_e64 v104, v216, v104, s[44:45]
	v_cndmask_b32_e64 v105, v216, v105, s[42:43]
	v_add_f32_e32 v107, v108, v107
	v_max3_f32 v121, v121, v104, v105
	v_cndmask_b32_e64 v106, v216, v106, s[40:41]
	v_cndmask_b32_e32 v107, v216, v107, vcc
	v_max3_f32 v108, v121, v106, v107
	ds_bpermute_b32 v110, v141, v108
	s_add_i32 s14, s14, 2
	s_add_u32 s70, s70, 0x100
	s_addc_u32 s71, s71, 0
	s_add_i32 s9, s9, 2
	s_waitcnt lgkmcnt(0)
	v_max_f32_e32 v110, v110, v110
	v_max_f32_e32 v108, v108, v110
	ds_bpermute_b32 v110, v142, v108
	s_cmp_eq_u32 s14, 4
	s_waitcnt lgkmcnt(0)
	v_max_f32_e32 v110, v110, v110
	v_max_f32_e32 v108, v108, v110
	v_sub_f32_e32 v3, v3, v108
	v_exp_f32_e32 v110, v3
	v_sub_f32_e32 v109, v109, v108
	v_exp_f32_e32 v109, v109
	v_sub_f32_e32 v111, v123, v108
	v_exp_f32_e32 v111, v111
	v_sub_f32_e32 v121, v125, v108
	v_exp_f32_e32 v191, v121
	v_sub_f32_e32 v121, v154, v108
	v_add_f32_e32 v3, 0, v110
	v_exp_f32_e32 v192, v121
	v_sub_f32_e32 v121, v155, v108
	v_add_f32_e32 v3, v109, v3
	v_exp_f32_e32 v193, v121
	v_sub_f32_e32 v121, v157, v108
	v_add_f32_e32 v3, v111, v3
	v_exp_f32_e32 v157, v121
	v_sub_f32_e32 v121, v158, v108
	v_add_f32_e32 v3, v191, v3
	v_exp_f32_e32 v158, v121
	v_sub_f32_e32 v121, v159, v108
	v_add_f32_e32 v3, v192, v3
	v_exp_f32_e32 v159, v121
	v_sub_f32_e32 v121, v160, v108
	v_add_f32_e32 v3, v193, v3
	v_exp_f32_e32 v160, v121
	v_sub_f32_e32 v121, v161, v108
	v_add_f32_e32 v3, v157, v3
	v_exp_f32_e32 v161, v121
	v_sub_f32_e32 v121, v170, v108
	v_add_f32_e32 v3, v158, v3
	v_exp_f32_e32 v198, v121
	v_sub_f32_e32 v121, v171, v108
	v_add_f32_e32 v3, v159, v3
	v_exp_f32_e32 v199, v121
	v_sub_f32_e32 v121, v172, v108
	v_add_f32_e32 v3, v160, v3
	v_exp_f32_e32 v200, v121
	v_sub_f32_e32 v121, v173, v108
	v_add_f32_e32 v3, v161, v3
	v_exp_f32_e32 v201, v121
	v_sub_f32_e32 v121, v174, v108
	v_add_f32_e32 v3, v198, v3
	v_exp_f32_e32 v202, v121
	v_sub_f32_e32 v121, v175, v108
	v_add_f32_e32 v3, v199, v3
	v_exp_f32_e32 v203, v121
	v_sub_f32_e32 v121, v176, v108
	v_add_f32_e32 v3, v200, v3
	v_exp_f32_e32 v204, v121
	v_sub_f32_e32 v121, v177, v108
	v_add_f32_e32 v3, v201, v3
	v_exp_f32_e32 v205, v121
	v_sub_f32_e32 v121, v178, v108
	v_add_f32_e32 v3, v202, v3
	v_exp_f32_e32 v206, v121
	v_sub_f32_e32 v121, v179, v108
	v_add_f32_e32 v3, v203, v3
	v_exp_f32_e32 v207, v121
	v_sub_f32_e32 v121, v180, v108
	v_add_f32_e32 v3, v204, v3
	v_exp_f32_e32 v219, v121
	v_sub_f32_e32 v121, v181, v108
	v_add_f32_e32 v3, v205, v3
	v_exp_f32_e32 v220, v121
	v_sub_f32_e32 v121, v182, v108
	v_add_f32_e32 v3, v206, v3
	v_exp_f32_e32 v221, v121
	v_sub_f32_e32 v121, v183, v108
	v_add_f32_e32 v3, v207, v3
	v_exp_f32_e32 v125, v121
	v_sub_f32_e32 v121, v184, v108
	v_add_f32_e32 v3, v219, v3
	v_exp_f32_e32 v154, v121
	v_sub_f32_e32 v121, v185, v108
	v_add_f32_e32 v3, v220, v3
	v_exp_f32_e32 v155, v121
	v_sub_f32_e32 v121, v186, v108
	v_add_f32_e32 v3, v221, v3
	v_exp_f32_e32 v222, v121
	v_sub_f32_e32 v121, v187, v108
	v_add_f32_e32 v3, v125, v3
	v_exp_f32_e32 v223, v121
	v_sub_f32_e32 v121, v188, v108
	v_add_f32_e32 v3, v154, v3
	v_exp_f32_e32 v224, v121
	v_sub_f32_e32 v121, v189, v108
	v_add_f32_e32 v3, v155, v3
	v_exp_f32_e32 v225, v121
	v_sub_f32_e32 v121, v190, v108
	v_add_f32_e32 v3, v222, v3
	v_exp_f32_e32 v226, v121
	v_sub_f32_e32 v104, v104, v108
	v_add_f32_e32 v3, v223, v3
	v_exp_f32_e32 v104, v104
	v_sub_f32_e32 v105, v105, v108
	v_add_f32_e32 v3, v224, v3
	v_exp_f32_e32 v105, v105
	v_sub_f32_e32 v106, v106, v108
	v_add_f32_e32 v3, v225, v3
	v_exp_f32_e32 v106, v106
	v_sub_f32_e32 v107, v107, v108
	v_add_f32_e32 v3, v226, v3
	v_exp_f32_e32 v107, v107
	v_add_f32_e32 v3, v104, v3
	v_add_f32_e32 v3, v105, v3
	v_add_f32_e32 v3, v106, v3
	v_add_f32_e32 v3, v107, v3
	ds_bpermute_b32 v121, v141, v3
	v_fma_f32 v1, v1, s65, -v108
	v_lshlrev_b32_e32 v108, 1, v0
	v_and_b32_e32 v174, 3, v0
	v_cvt_pk_bf16_f32 v0, v104, v105
	v_and_or_b32 v104, v108, s67, v174
	v_mul_lo_u32 v104, v104, s94
	v_cvt_pk_bf16_f32 v173, v157, v158
	v_and_b32_e32 v157, 24, v108
	v_xor_b32_e32 v157, v130, v157
	v_add3_u32 v157, v143, v157, v104
	v_add_u32_e32 v158, 0x9000, v157
	s_waitcnt lgkmcnt(0)
	v_add_f32_e32 v3, v3, v121
	v_exp_f32_e32 v121, v1
	v_cvt_pk_bf16_f32 v1, v106, v107
	ds_read2_b64 v[104:107], v158 offset1:4
	v_cvt_pk_bf16_f32 v170, v110, v109
	v_cvt_pk_bf16_f32 v171, v111, v191
	v_cvt_pk_bf16_f32 v172, v192, v193
	v_add_u32_e32 v227, 0x9800, v157
	ds_read2_b64 v[178:181], v227 offset0:12 offset1:16
	s_waitcnt lgkmcnt(1)
	v_mfma_f32_16x16x32_bf16 v[174:177], v[104:107], v[170:173], 0
	v_add_u32_e32 v104, 0x9100, v157
	ds_read2_b64 v[108:111], v104 offset1:232
	s_waitcnt lgkmcnt(1)
	v_mov_b32_e32 v106, v178
	v_mov_b32_e32 v107, v179
	v_mov_b32_e32 v178, v180
	v_mov_b32_e32 v179, v181
	s_waitcnt lgkmcnt(0)
	v_mov_b32_e32 v104, v110
	v_mov_b32_e32 v105, v111
	v_add_u32_e32 v110, 0xd000, v157
	v_add_u32_e32 v111, 0xd800, v157
	v_mfma_f32_16x16x32_bf16 v[182:185], v[104:107], v[170:173], 0
	ds_read2_b64 v[104:107], v110 offset0:64 offset1:68
	ds_read2_b64 v[190:193], v111 offset0:76 offset1:80
	ds_bpermute_b32 v123, v142, v3
	s_waitcnt lgkmcnt(2)
	v_mfma_f32_16x16x32_bf16 v[186:189], v[104:107], v[170:173], 0
	v_add_u32_e32 v104, 0xd300, v157
	ds_read2_b64 v[104:107], v104 offset1:232
	s_waitcnt lgkmcnt(2)
	v_mov_b32_e32 v196, v190
	v_mov_b32_e32 v197, v191
	v_mov_b32_e32 v190, v192
	v_mov_b32_e32 v191, v193
	s_waitcnt lgkmcnt(0)
	v_mov_b32_e32 v194, v106
	v_mov_b32_e32 v195, v107
	v_mov_b32_e32 v106, v104
	v_mov_b32_e32 v107, v105
	v_mfma_f32_16x16x32_bf16 v[170:173], v[194:197], v[170:173], 0
	v_cvt_pk_bf16_f32 v195, v161, v198
	v_cvt_pk_bf16_f32 v196, v199, v200
	v_cvt_pk_bf16_f32 v197, v201, v202
	ds_read2_b64 v[198:201], v158 offset0:8 offset1:12
	v_cvt_pk_bf16_f32 v194, v159, v160
	v_add_f32_e32 v123, v3, v123
	v_mov_b32_e32 v3, v2
	s_waitcnt lgkmcnt(0)
	v_mfma_f32_16x16x32_bf16 v[174:177], v[198:201], v[194:197], v[174:177]
	ds_read2_b64 v[198:201], v227 offset0:20 offset1:24
	v_lshl_add_u64 v[130:131], v[130:131], 1, v[132:133]
	s_waitcnt lgkmcnt(0)
	v_mov_b32_e32 v180, v198
	v_mov_b32_e32 v181, v199
	v_mov_b32_e32 v198, v200
	v_mov_b32_e32 v199, v201
	v_mfma_f32_16x16x32_bf16 v[178:181], v[178:181], v[194:197], v[182:185]
	s_nop 2
	ds_read2_b64 v[182:185], v110 offset0:72 offset1:76
	s_waitcnt lgkmcnt(0)
	v_mfma_f32_16x16x32_bf16 v[182:185], v[182:185], v[194:197], v[186:189]
	s_nop 2
	ds_read2_b64 v[186:189], v111 offset0:84 offset1:88
	s_waitcnt lgkmcnt(0)
	v_mov_b32_e32 v192, v186
	v_mov_b32_e32 v193, v187
	v_mov_b32_e32 v186, v188
	v_mov_b32_e32 v187, v189
	v_mfma_f32_16x16x32_bf16 v[170:173], v[190:193], v[194:197], v[170:173]
	ds_read2_b64 v[194:197], v158 offset0:16 offset1:20
	v_cvt_pk_bf16_f32 v190, v203, v204
	v_cvt_pk_bf16_f32 v191, v205, v206
	v_cvt_pk_bf16_f32 v192, v207, v219
	v_cvt_pk_bf16_f32 v193, v220, v221
	s_waitcnt lgkmcnt(0)
	s_nop 0
	v_mfma_f32_16x16x32_bf16 v[174:177], v[194:197], v[190:193], v[174:177]
	ds_read2_b64 v[194:197], v227 offset0:28 offset1:32
	s_waitcnt lgkmcnt(0)
	v_mov_b32_e32 v200, v194
	v_mov_b32_e32 v201, v195
	v_mov_b32_e32 v194, v196
	v_mov_b32_e32 v195, v197
	v_mfma_f32_16x16x32_bf16 v[178:181], v[198:201], v[190:193], v[178:181]
	ds_read2_b64 v[198:201], v110 offset0:80 offset1:84
	s_waitcnt lgkmcnt(0)
	v_mfma_f32_16x16x32_bf16 v[182:185], v[198:201], v[190:193], v[182:185]
	ds_read2_b64 v[198:201], v111 offset0:92 offset1:96
	s_waitcnt lgkmcnt(0)
	v_mov_b32_e32 v188, v198
	v_mov_b32_e32 v189, v199
	v_mov_b32_e32 v198, v200
	v_mov_b32_e32 v199, v201
	v_mfma_f32_16x16x32_bf16 v[170:173], v[186:189], v[190:193], v[170:173]
	ds_read2_b64 v[190:193], v158 offset0:24 offset1:28
	v_cvt_pk_bf16_f32 v186, v125, v154
	v_cvt_pk_bf16_f32 v187, v155, v222
	v_cvt_pk_bf16_f32 v188, v223, v224
	v_cvt_pk_bf16_f32 v189, v225, v226
	s_waitcnt lgkmcnt(0)
	s_nop 0
	v_mfma_f32_16x16x32_bf16 v[174:177], v[190:193], v[186:189], v[174:177]
	ds_read2_b64 v[190:193], v227 offset0:36 offset1:40
	s_waitcnt lgkmcnt(0)
	v_mov_b32_e32 v196, v190
	v_mov_b32_e32 v197, v191
	v_mov_b32_e32 v190, v192
	v_mov_b32_e32 v191, v193
	v_mfma_f32_16x16x32_bf16 v[178:181], v[194:197], v[186:189], v[178:181]
	ds_read2_b64 v[194:197], v110 offset0:88 offset1:92
	v_mov_b32_e32 v110, v108
	s_waitcnt lgkmcnt(0)
	v_mfma_f32_16x16x32_bf16 v[182:185], v[194:197], v[186:189], v[182:185]
	ds_read2_b64 v[194:197], v111 offset0:100 offset1:104
	v_mov_b32_e32 v111, v109
	s_waitcnt lgkmcnt(0)
	v_mov_b32_e32 v200, v194
	v_mov_b32_e32 v201, v195
	v_mov_b32_e32 v194, v196
	v_mov_b32_e32 v195, v197
	v_mfma_f32_16x16x32_bf16 v[170:173], v[198:201], v[186:189], v[170:173]
	v_mfma_f32_16x16x32_bf16 v[108:111], v[108:111], v[0:3], v[174:177]
	v_mfma_f32_16x16x32_bf16 v[174:177], v[190:193], v[0:3], v[178:181]
	v_mfma_f32_16x16x32_bf16 v[104:107], v[104:107], v[0:3], v[182:185]
	v_mfma_f32_16x16x32_bf16 v[170:173], v[194:197], v[0:3], v[170:173]
	v_add_f32_e32 v0, v121, v123
	v_div_scale_f32 v1, s[40:41], v0, v0, 1.0
	v_rcp_f32_e32 v3, v1
	s_mov_b64 s[40:41], 0x7e00400
	v_lshl_add_u64 v[132:133], v[130:131], 0, s[40:41]
	v_fma_f32 v121, -v1, v3, 1.0
	v_fmac_f32_e32 v3, v121, v3
	v_div_scale_f32 v121, vcc, 1.0, v0, 1.0
	v_mul_f32_e32 v123, v121, v3
	v_fma_f32 v125, -v1, v123, v121
	v_fmac_f32_e32 v123, v125, v3
	v_fma_f32 v1, -v1, v123, v121
	v_div_fmas_f32 v1, v1, v3, v123
	v_div_fixup_f32 v0, v1, v0, 1.0
	v_pk_mul_f32 v[108:109], v[108:109], v[0:1] op_sel_hi:[1,0]
	v_pk_mul_f32 v[110:111], v[110:111], v[0:1] op_sel_hi:[1,0]
	v_pk_mul_f32 v[104:105], v[104:105], v[0:1] op_sel_hi:[1,0]
	v_pk_mul_f32 v[106:107], v[106:107], v[0:1] op_sel_hi:[1,0]
	v_cvt_pk_bf16_f32 v108, v108, v109
	v_cvt_pk_bf16_f32 v109, v110, v111
	v_pk_mul_f32 v[110:111], v[174:175], v[0:1] op_sel_hi:[1,0]
	v_pk_mul_f32 v[134:135], v[176:177], v[0:1] op_sel_hi:[1,0]
	v_add_co_u32_e32 v130, vcc, s74, v130
	v_cvt_pk_bf16_f32 v104, v104, v105
	v_cvt_pk_bf16_f32 v105, v106, v107
	v_pk_mul_f32 v[106:107], v[170:171], v[0:1] op_sel_hi:[1,0]
	v_pk_mul_f32 v[0:1], v[172:173], v[0:1] op_sel_hi:[1,0]
	v_cvt_pk_bf16_f32 v110, v110, v111
	v_cvt_pk_bf16_f32 v111, v134, v135
	v_addc_co_u32_e32 v131, vcc, 0, v131, vcc
	v_cvt_pk_bf16_f32 v106, v106, v107
	v_cvt_pk_bf16_f32 v107, v0, v1
	global_store_dwordx4 v[130:131], v[108:111], off offset:1024 nt
	global_store_dwordx4 v[132:133], v[104:107], off offset:64 nt
	s_cbranch_scc1 .LBB0_425
.LBB0_429:
	s_waitcnt vmcnt(3)
	v_lshlrev_b32_e32 v170, 16, v96
	v_and_b32_e32 v171, 0xffff0000, v96
	v_lshlrev_b32_e32 v158, 16, v97
	v_and_b32_e32 v159, 0xffff0000, v97
	v_pk_mul_f32 v[96:97], v[170:171], v[170:171]
	v_pk_mul_f32 v[160:161], v[158:159], v[158:159]
	v_add_f32_e32 v3, v96, v97
	v_lshlrev_b32_e32 v154, 16, v98
	v_and_b32_e32 v155, 0xffff0000, v98
	v_add_f32_e32 v3, v160, v3
	v_lshlrev_b32_e32 v132, 16, v99
	v_and_b32_e32 v133, 0xffff0000, v99
	v_pk_mul_f32 v[98:99], v[154:155], v[154:155]
	v_add_f32_e32 v3, v161, v3
	v_add_f32_e32 v3, v98, v3
	v_pk_mul_f32 v[134:135], v[132:133], v[132:133]
	v_add_f32_e32 v3, v99, v3
	s_waitcnt vmcnt(2)
	v_lshlrev_b32_e32 v130, 16, v100
	v_and_b32_e32 v131, 0xffff0000, v100
	v_add_f32_e32 v3, v134, v3
	v_lshlrev_b32_e32 v110, 16, v101
	v_and_b32_e32 v111, 0xffff0000, v101
	v_pk_mul_f32 v[100:101], v[130:131], v[130:131]
	v_add_f32_e32 v3, v135, v3
	v_add_f32_e32 v3, v100, v3
	v_pk_mul_f32 v[106:107], v[110:111], v[110:111]
	v_add_f32_e32 v3, v101, v3
	v_lshlrev_b32_e32 v108, 16, v102
	v_and_b32_e32 v109, 0xffff0000, v102
	v_add_f32_e32 v3, v106, v3
	v_lshlrev_b32_e32 v0, 16, v103
	v_and_b32_e32 v1, 0xffff0000, v103
	v_pk_mul_f32 v[102:103], v[108:109], v[108:109]
	v_add_f32_e32 v3, v107, v3
	v_add_f32_e32 v3, v102, v3
	v_pk_mul_f32 v[104:105], v[0:1], v[0:1]
	v_add_f32_e32 v3, v103, v3
	v_add_f32_e32 v3, v104, v3
	v_add_f32_e32 v3, v105, v3
	ds_bpermute_b32 v96, v141, v3
	s_add_u32 s72, s12, s70
	s_addc_u32 s73, s13, s71
	s_add_i32 s40, s9, -1
	s_waitcnt lgkmcnt(0)
	v_add_f32_e32 v3, v3, v96
	ds_bpermute_b32 v96, v142, v3
	s_waitcnt lgkmcnt(0)
	v_add_f32_e32 v3, v3, v96
	v_fmamk_f32 v3, v3, 0x3c800000, v209
	v_mul_f32_e32 v96, 0x4b800000, v3
	v_cmp_gt_f32_e32 vcc, s68, v3
	s_nop 1
	v_cndmask_b32_e32 v3, v3, v96, vcc
	v_rsq_f32_e32 v3, v3
	s_nop 0
	v_mul_f32_e32 v96, 0x45800000, v3
	v_cndmask_b32_e32 v3, v3, v96, vcc
	v_mul_f32_e32 v100, 0x3e38aa3b, v3
	v_pk_mul_f32 v[96:97], v[100:101], v[170:171] op_sel_hi:[0,1]
	s_waitcnt vmcnt(4)
	v_pk_mul_f32 v[96:97], v[4:5], v[96:97]
	v_pk_mul_f32 v[0:1], v[100:101], v[0:1] op_sel_hi:[0,1]
	v_cvt_pk_bf16_f32 v102, v96, v97
	v_pk_mul_f32 v[96:97], v[100:101], v[158:159] op_sel_hi:[0,1]
	v_pk_mul_f32 v[96:97], v[6:7], v[96:97]
	s_waitcnt vmcnt(1)
	v_pk_mul_f32 v[0:1], v[18:19], v[0:1]
	v_cvt_pk_bf16_f32 v103, v96, v97
	v_pk_mul_f32 v[96:97], v[100:101], v[154:155] op_sel_hi:[0,1]
	v_pk_mul_f32 v[96:97], v[8:9], v[96:97]
	v_mov_b32_e32 v3, v113
	v_cvt_pk_bf16_f32 v104, v96, v97
	v_pk_mul_f32 v[96:97], v[100:101], v[132:133] op_sel_hi:[0,1]
	v_pk_mul_f32 v[96:97], v[10:11], v[96:97]
	s_nop 0
	v_cvt_pk_bf16_f32 v105, v96, v97
	v_pk_mul_f32 v[96:97], v[100:101], v[130:131] op_sel_hi:[0,1]
	v_pk_mul_f32 v[96:97], v[12:13], v[96:97]
	v_mfma_f32_16x16x32_bf16 v[194:197], v[80:83], v[102:105], 0
	v_cvt_pk_bf16_f32 v106, v96, v97
	v_pk_mul_f32 v[96:97], v[100:101], v[110:111] op_sel_hi:[0,1]
	v_pk_mul_f32 v[96:97], v[14:15], v[96:97]
	s_nop 0
	v_cvt_pk_bf16_f32 v107, v96, v97
	v_pk_mul_f32 v[96:97], v[100:101], v[108:109] op_sel_hi:[0,1]
	v_pk_mul_f32 v[96:97], v[16:17], v[96:97]
	v_cvt_pk_bf16_f32 v109, v0, v1
	v_cvt_pk_bf16_f32 v108, v96, v97
	v_mfma_f32_16x16x32_bf16 v[96:99], v[24:27], v[102:105], 0
	v_mov_b32_e32 v100, v112
	v_mfma_f32_16x16x32_bf16 v[130:133], v[28:31], v[106:109], v[96:99]
	v_lshlrev_b32_e32 v0, 3, v3
	v_ashrrev_i32_e32 v1, 31, v0
	v_ashrrev_i32_e32 v101, 31, v100
	v_mfma_f32_16x16x32_bf16 v[96:99], v[32:35], v[102:105], 0
	v_lshlrev_b32_e32 v3, 2, v3
	v_sub_u32_e32 v3, v100, v3
	v_cmp_gt_i32_e64 s[48:49], 0, v3
	v_mfma_f32_16x16x32_bf16 v[170:173], v[36:39], v[106:109], v[96:99]
	v_cmp_gt_i32_e64 s[50:51], 1, v3
	v_cmp_gt_i32_e64 s[52:53], 2, v3
	v_cmp_gt_i32_e64 s[54:55], 3, v3
	v_mfma_f32_16x16x32_bf16 v[96:99], v[40:43], v[102:105], 0
	v_cmp_lt_i32_e64 s[44:45], -1, v3
	v_cmp_lt_i32_e64 s[42:43], 0, v3
	v_mfma_f32_16x16x32_bf16 v[174:177], v[44:47], v[106:109], v[96:99]
	v_mfma_f32_16x16x32_bf16 v[96:99], v[48:51], v[102:105], 0
	v_mfma_f32_16x16x32_bf16 v[178:181], v[52:55], v[106:109], v[96:99]
	v_mfma_f32_16x16x32_bf16 v[96:99], v[56:59], v[102:105], 0
	v_mfma_f32_16x16x32_bf16 v[182:185], v[60:63], v[106:109], v[96:99]
	v_mfma_f32_16x16x32_bf16 v[96:99], v[64:67], v[102:105], 0
	v_mfma_f32_16x16x32_bf16 v[186:189], v[68:71], v[106:109], v[96:99]
	v_mfma_f32_16x16x32_bf16 v[96:99], v[72:75], v[102:105], 0
	v_mfma_f32_16x16x32_bf16 v[190:193], v[76:79], v[106:109], v[96:99]
	v_mfma_f32_16x16x32_bf16 v[102:105], v[88:91], v[102:105], 0
	s_nop 5
	v_lshlrev_b64 v[98:99], 1, v[0:1]
	v_cvt_f32_u32_e32 v1, s40
	v_lshl_add_u64 v[96:97], v[126:127], 0, v[100:101]
	v_mad_u64_u32 v[110:111], s[40:41], v96, s62, v[98:99]
	v_cmp_lt_f32_e32 vcc, s57, v1
	s_and_b64 s[40:41], vcc, exec
	s_cselect_b32 s40, 0xffffffc0, 0
	v_cndmask_b32_e32 v101, 0, v215, vcc
	v_sub_f32_e32 v1, v101, v1
	v_exp_f32_e32 v1, v1
	v_cmp_lt_i32_e32 vcc, 2, v3
	s_cmp_eq_u32 s70, 0
	v_mfma_f32_16x16x32_bf16 v[194:197], v[84:87], v[106:109], v[194:197]
	v_ldexp_f32 v1, v1, s40
	v_cmp_lt_i32_e64 s[40:41], 1, v3
	v_add_u32_e32 v3, 0x80, v3
	v_cvt_f32_i32_e32 v157, v3
	v_mfma_f32_16x16x32_bf16 v[102:105], v[92:95], v[106:109], v[102:105]
	v_mul_f32_e32 v106, 0x3fb8aa3b, v1
	s_cselect_b64 s[46:47], -1, 0
	s_cmp_eq_u32 s14, 2
	s_cselect_b64 s[56:57], -1, 0
	v_pk_mul_f32 v[108:109], v[106:107], v[156:157] op_sel_hi:[0,1]
	s_waitcnt vmcnt(0)
	v_cndmask_b32_e64 v3, v23, v22, s[56:57]
	v_fma_f32 v107, v106, 0, -v109
	v_cndmask_b32_e64 v101, v3, v20, s[46:47]
	v_add_f32_e32 v107, v107, v130
	s_and_b64 s[46:47], s[78:79], s[48:49]
	v_fma_f32 v1, v1, s65, -v109
	v_cndmask_b32_e64 v121, v216, v107, s[46:47]
	v_add_f32_e32 v1, v1, v131
	s_and_b64 s[46:47], s[78:79], s[50:51]
	v_fma_f32 v107, v106, 2.0, -v109
	v_cndmask_b32_e64 v1, v216, v1, s[46:47]
	v_add_f32_e32 v107, v107, v132
	s_and_b64 s[46:47], s[78:79], s[52:53]
	v_cndmask_b32_e64 v123, v216, v107, s[46:47]
	v_fma_f32 v107, v106, s17, -v109
	v_add_f32_e32 v107, v107, v133
	s_and_b64 s[46:47], s[78:79], s[54:55]
	v_cndmask_b32_e64 v125, v216, v107, s[46:47]
	v_fma_f32 v107, v106, s18, -v109
	v_add_f32_e32 v107, v107, v170
	v_cndmask_b32_e64 v130, v216, v107, s[24:25]
	v_fma_f32 v107, v106, s19, -v109
	v_add_f32_e32 v107, v107, v171
	v_cndmask_b32_e64 v131, v216, v107, s[24:25]
	v_fma_f32 v107, v106, s20, -v109
	v_add_f32_e32 v107, v107, v172
	v_cndmask_b32_e64 v132, v216, v107, s[24:25]
	v_fma_f32 v107, v106, s21, -v109
	v_add_f32_e32 v107, v107, v173
	v_cndmask_b32_e64 v133, v216, v107, s[24:25]
	v_fma_f32 v107, v106, s22, -v109
	v_add_f32_e32 v107, v107, v174
	v_cndmask_b32_e64 v135, v216, v107, s[26:27]
	v_fma_f32 v107, v106, s0, -v109
	v_add_f32_e32 v107, v107, v175
	v_cndmask_b32_e64 v154, v216, v107, s[26:27]
	v_fma_f32 v107, v106, s33, -v109
	v_add_f32_e32 v107, v107, v176
	v_cndmask_b32_e64 v155, v216, v107, s[26:27]
	v_fma_f32 v107, v106, s61, -v109
	v_add_f32_e32 v107, v107, v177
	v_cndmask_b32_e64 v157, v216, v107, s[26:27]
	v_fma_f32 v107, v106, s4, -v109
	v_add_f32_e32 v107, v107, v178
	v_cndmask_b32_e64 v158, v216, v107, s[28:29]
	v_fma_f32 v107, v106, s81, -v109
	v_add_f32_e32 v107, v107, v179
	v_cndmask_b32_e64 v159, v216, v107, s[28:29]
	v_fma_f32 v107, v106, s69, -v109
	v_add_f32_e32 v107, v107, v180
	v_cndmask_b32_e64 v160, v216, v107, s[28:29]
	v_fma_f32 v107, v106, s59, -v109
	v_add_f32_e32 v107, v107, v181
	v_cndmask_b32_e64 v161, v216, v107, s[28:29]
	v_fma_f32 v107, v106, s16, -v109
	v_add_f32_e32 v107, v107, v182
	v_cndmask_b32_e64 v170, v216, v107, s[30:31]
	v_fma_f32 v107, v106, s58, -v109
	v_add_f32_e32 v107, v107, v183
	v_cndmask_b32_e64 v171, v216, v107, s[30:31]
	v_fma_f32 v107, v106, s64, -v109
	v_add_f32_e32 v107, v107, v184
	v_cndmask_b32_e64 v172, v216, v107, s[30:31]
	v_fma_f32 v107, v106, s3, -v109
	v_add_f32_e32 v107, v107, v185
	v_cndmask_b32_e64 v173, v216, v107, s[30:31]
	v_fma_f32 v107, v106, s2, -v109
	v_add_f32_e32 v107, v107, v186
	v_cndmask_b32_e64 v174, v216, v107, s[34:35]
	v_fma_f32 v107, v106, s63, -v109
	v_add_f32_e32 v107, v107, v187
	v_cndmask_b32_e64 v175, v216, v107, s[34:35]
	v_fma_f32 v107, v106, s82, -v109
	v_add_f32_e32 v107, v107, v188
	v_cndmask_b32_e64 v176, v216, v107, s[34:35]
	v_fma_f32 v107, v106, s83, -v109
	v_add_f32_e32 v107, v107, v189
	v_cndmask_b32_e64 v177, v216, v107, s[34:35]
	v_fma_f32 v107, v106, s80, -v109
	v_add_f32_e32 v107, v107, v190
	v_cndmask_b32_e64 v178, v216, v107, s[36:37]
	v_fma_f32 v107, v106, s90, -v109
	v_add_f32_e32 v107, v107, v191
	v_cndmask_b32_e64 v179, v216, v107, s[36:37]
	v_fma_f32 v107, v106, s91, -v109
	v_add_f32_e32 v107, v107, v192
	v_cndmask_b32_e64 v180, v216, v107, s[36:37]
	v_fma_f32 v107, v106, s88, -v109
	v_mul_f32_e32 v3, 0x3fb8aa3b, v101
	v_add_f32_e32 v107, v107, v193
	v_max3_f32 v3, v3, v121, v1
	v_cndmask_b32_e64 v181, v216, v107, s[36:37]
	v_fma_f32 v107, v106, s89, -v109
	v_max3_f32 v3, v3, v123, v125
	v_add_f32_e32 v107, v107, v194
	v_max3_f32 v3, v3, v130, v131
	v_cndmask_b32_e64 v182, v216, v107, s[38:39]
	v_fma_f32 v107, v106, s75, -v109
	v_max3_f32 v3, v3, v132, v133
	v_add_f32_e32 v107, v107, v195
	v_max3_f32 v3, v3, v135, v154
	v_cndmask_b32_e64 v183, v216, v107, s[38:39]
	v_fma_f32 v107, v106, s96, -v109
	v_max3_f32 v3, v3, v155, v157
	v_add_f32_e32 v107, v107, v196
	v_max3_f32 v3, v3, v158, v159
	v_cndmask_b32_e64 v184, v216, v107, s[38:39]
	v_fma_f32 v107, v106, s97, -v109
	v_max3_f32 v3, v3, v160, v161
	v_add_f32_e32 v107, v107, v197
	v_max3_f32 v3, v3, v170, v171
	v_cndmask_b32_e64 v185, v216, v107, s[38:39]
	v_fma_f32 v107, v106, s5, -v109
	v_max3_f32 v3, v3, v172, v173
	v_add_f32_e32 v102, v107, v102
	s_and_b64 s[44:45], s[84:85], s[44:45]
	v_max3_f32 v3, v3, v174, v175
	v_cndmask_b32_e64 v186, v216, v102, s[44:45]
	v_fma_f32 v102, v106, s60, -v109
	v_max3_f32 v3, v3, v176, v177
	v_add_f32_e32 v102, v102, v103
	s_and_b64 s[42:43], s[84:85], s[42:43]
	v_max3_f32 v3, v3, v178, v179
	v_cndmask_b32_e64 v198, v216, v102, s[42:43]
	v_fma_f32 v102, v106, s66, -v109
	v_max3_f32 v3, v3, v180, v181
	v_add_f32_e32 v102, v102, v104
	s_and_b64 s[40:41], s[84:85], s[40:41]
	v_max3_f32 v3, v3, v182, v183
	v_cndmask_b32_e64 v206, v216, v102, s[40:41]
	v_sub_f32_e32 v102, v108, v109
	v_max3_f32 v3, v3, v184, v185
	v_add_f32_e32 v102, v102, v105
	s_and_b64 vcc, s[84:85], vcc
	v_max3_f32 v3, v3, v186, v198
	v_cndmask_b32_e32 v207, v216, v102, vcc
	v_max3_f32 v3, v3, v206, v207
	ds_bpermute_b32 v104, v141, v3
	v_mov_b32_e32 v134, v111
	v_mad_u64_u32 v[102:103], s[40:41], v97, s62, v[134:135]
	v_mov_b32_e32 v111, v102
	s_waitcnt lgkmcnt(0)
	v_max_f32_e32 v104, v104, v104
	v_max_f32_e32 v3, v3, v104
	ds_bpermute_b32 v134, v142, v3
	v_lshl_add_u64 v[102:103], s[72:73], 0, v[110:111]
	s_mov_b32 s40, 0xbe00000
	v_add_co_u32_e32 v102, vcc, s40, v102
	v_lshlrev_b64 v[96:97], 11, v[96:97]
	s_nop 0
	v_addc_co_u32_e32 v103, vcc, 0, v103, vcc
	global_load_dwordx4 v[104:107], v[102:103], off offset:3200
	global_load_dwordx4 v[108:111], v[102:103], off offset:3264
	s_waitcnt lgkmcnt(0)
	v_max_f32_e32 v102, v134, v134
	v_max_f32_e32 v102, v3, v102
	v_sub_f32_e32 v3, v121, v102
	v_sub_f32_e32 v121, v125, v102
	v_sub_f32_e32 v125, v130, v102
	v_sub_f32_e32 v130, v131, v102
	v_exp_f32_e32 v134, v130
	v_sub_f32_e32 v130, v132, v102
	v_exp_f32_e32 v187, v130
	v_sub_f32_e32 v130, v133, v102
	v_exp_f32_e32 v188, v130
	v_sub_f32_e32 v130, v135, v102
	v_exp_f32_e32 v135, v130
	v_sub_f32_e32 v130, v154, v102
	v_exp_f32_e32 v154, v130
	v_sub_f32_e32 v130, v155, v102
	v_exp_f32_e32 v155, v130
	v_sub_f32_e32 v130, v157, v102
	v_exp_f32_e32 v157, v130
	v_sub_f32_e32 v130, v158, v102
	v_exp_f32_e32 v158, v130
	v_sub_f32_e32 v130, v159, v102
	v_exp_f32_e32 v159, v130
	v_sub_f32_e32 v130, v160, v102
	v_exp_f32_e32 v160, v130
	v_sub_f32_e32 v130, v161, v102
	v_exp_f32_e32 v161, v130
	v_sub_f32_e32 v130, v170, v102
	v_exp_f32_e32 v219, v130
	v_sub_f32_e32 v130, v171, v102
	v_exp_f32_e32 v224, v130
	v_sub_f32_e32 v130, v172, v102
	v_exp_f32_e32 v225, v130
	v_sub_f32_e32 v130, v173, v102
	v_exp_f32_e32 v226, v130
	v_sub_f32_e32 v130, v174, v102
	v_exp_f32_e32 v227, v130
	v_sub_f32_e32 v130, v175, v102
	v_exp_f32_e32 v228, v130
	v_sub_f32_e32 v130, v176, v102
	v_exp_f32_e32 v229, v130
	v_sub_f32_e32 v130, v177, v102
	v_exp_f32_e32 v230, v130
	v_sub_f32_e32 v130, v178, v102
	v_exp_f32_e32 v231, v130
	v_sub_f32_e32 v130, v179, v102
	v_exp_f32_e32 v232, v130
	v_sub_f32_e32 v130, v180, v102
	v_exp_f32_e32 v233, v130
	v_sub_f32_e32 v130, v181, v102
	v_exp_f32_e32 v234, v130
	v_sub_f32_e32 v130, v182, v102
	v_exp_f32_e32 v235, v130
	v_sub_f32_e32 v130, v183, v102
	v_exp_f32_e32 v3, v3
	v_sub_f32_e32 v1, v1, v102
	v_exp_f32_e32 v236, v130
	v_sub_f32_e32 v130, v184, v102
	v_exp_f32_e32 v1, v1
	v_sub_f32_e32 v103, v123, v102
	v_exp_f32_e32 v237, v130
	v_sub_f32_e32 v130, v185, v102
	v_exp_f32_e32 v103, v103
	v_exp_f32_e32 v238, v130
	v_sub_f32_e32 v130, v186, v102
	v_exp_f32_e32 v121, v121
	v_exp_f32_e32 v239, v130
	v_lshlrev_b32_e32 v130, 1, v100
	v_and_b32_e32 v100, 3, v100
	v_add_f32_e32 v123, 0, v3
	v_exp_f32_e32 v125, v125
	v_and_or_b32 v100, v130, s67, v100
	v_add_f32_e32 v123, v1, v123
	v_mul_lo_u32 v100, v100, s94
	v_add_f32_e32 v123, v103, v123
	v_and_b32_e32 v130, 24, v130
	v_xor_b32_e32 v0, v0, v130
	v_add3_u32 v0, v143, v0, v100
	v_add_f32_e32 v123, v121, v123
	v_add_u32_e32 v100, 0x9000, v0
	v_add_f32_e32 v123, v125, v123
	ds_read2_b64 v[130:133], v100 offset1:4
	v_add_f32_e32 v123, v134, v123
	v_cvt_pk_bf16_f32 v170, v3, v1
	v_add_u32_e32 v1, 0x9100, v0
	v_add_f32_e32 v123, v187, v123
	v_cvt_pk_bf16_f32 v171, v103, v121
	ds_read2_b64 v[174:177], v1 offset1:232
	v_add_u32_e32 v1, 0x9800, v0
	v_add_u32_e32 v3, 0xd000, v0
	v_add_u32_e32 v103, 0xd300, v0
	v_add_u32_e32 v0, 0xd800, v0
	v_add_f32_e32 v123, v188, v123
	ds_read2_b64 v[178:181], v1 offset0:12 offset1:16
	v_cvt_pk_bf16_f32 v173, v187, v188
	ds_read2_b64 v[182:185], v3 offset0:64 offset1:68
	ds_read2_b64 v[186:189], v103 offset1:232
	ds_read2_b64 v[190:193], v0 offset0:76 offset1:80
	ds_read2_b64 v[194:197], v100 offset0:8 offset1:12
	v_cvt_pk_bf16_f32 v172, v125, v134
	v_sub_f32_e32 v121, v198, v102
	ds_read2_b64 v[198:201], v1 offset0:20 offset1:24
	s_waitcnt lgkmcnt(7)
	v_mfma_f32_16x16x32_bf16 v[130:133], v[130:133], v[170:173], 0
	v_add_f32_e32 v123, v135, v123
	v_add_f32_e32 v123, v154, v123
	v_add_f32_e32 v123, v155, v123
	s_waitcnt lgkmcnt(5)
	v_mfma_f32_16x16x32_bf16 v[176:179], v[176:179], v[170:173], 0
	v_add_f32_e32 v123, v157, v123
	v_add_f32_e32 v123, v158, v123
	v_add_f32_e32 v123, v159, v123
	s_waitcnt lgkmcnt(4)
	v_mfma_f32_16x16x32_bf16 v[182:185], v[182:185], v[170:173], 0
	v_add_f32_e32 v123, v160, v123
	ds_read2_b64 v[220:223], v0 offset0:84 offset1:88
	v_add_f32_e32 v123, v161, v123
	s_waitcnt lgkmcnt(3)
	v_mfma_f32_16x16x32_bf16 v[170:173], v[188:191], v[170:173], 0
	v_cvt_pk_bf16_f32 v188, v135, v154
	v_cvt_pk_bf16_f32 v189, v155, v157
	v_cvt_pk_bf16_f32 v190, v158, v159
	v_cvt_pk_bf16_f32 v191, v160, v161
	ds_read2_b64 v[202:205], v3 offset0:72 offset1:76
	v_add_f32_e32 v123, v219, v123
	s_waitcnt lgkmcnt(3)
	v_mfma_f32_16x16x32_bf16 v[130:133], v[194:197], v[188:191], v[130:133]
	v_mov_b32_e32 v194, v180
	v_mov_b32_e32 v195, v181
	s_waitcnt lgkmcnt(2)
	v_mov_b32_e32 v196, v198
	v_mov_b32_e32 v197, v199
	v_add_f32_e32 v123, v224, v123
	v_add_f32_e32 v123, v225, v123
	v_mfma_f32_16x16x32_bf16 v[176:179], v[194:197], v[188:191], v[176:179]
	ds_read2_b64 v[196:199], v100 offset0:16 offset1:20
	v_add_f32_e32 v123, v226, v123
	s_waitcnt lgkmcnt(2)
	v_mov_b32_e32 v194, v220
	v_mov_b32_e32 v195, v221
	v_add_f32_e32 v123, v227, v123
	v_add_f32_e32 v123, v228, v123
	v_add_f32_e32 v123, v229, v123
	v_add_f32_e32 v123, v230, v123
	v_add_f32_e32 v123, v231, v123
	s_waitcnt lgkmcnt(1)
	v_mfma_f32_16x16x32_bf16 v[180:183], v[202:205], v[188:191], v[182:185]
	v_add_f32_e32 v123, v232, v123
	v_add_f32_e32 v123, v233, v123
	v_add_f32_e32 v123, v234, v123
	v_mfma_f32_16x16x32_bf16 v[170:173], v[192:195], v[188:191], v[170:173]
	v_cvt_pk_bf16_f32 v188, v219, v224
	v_cvt_pk_bf16_f32 v189, v225, v226
	v_cvt_pk_bf16_f32 v190, v227, v228
	v_cvt_pk_bf16_f32 v191, v229, v230
	ds_read2_b64 v[192:195], v1 offset0:28 offset1:32
	v_add_f32_e32 v123, v235, v123
	s_waitcnt lgkmcnt(1)
	v_mfma_f32_16x16x32_bf16 v[130:133], v[196:199], v[188:191], v[130:133]
	v_mov_b32_e32 v196, v200
	v_mov_b32_e32 v197, v201
	ds_read2_b64 v[200:203], v3 offset0:80 offset1:84
	v_add_f32_e32 v123, v236, v123
	v_add_f32_e32 v123, v237, v123
	v_add_f32_e32 v123, v238, v123
	v_add_f32_e32 v103, v239, v123
	v_exp_f32_e32 v121, v121
	v_sub_f32_e32 v123, v206, v102
	s_waitcnt lgkmcnt(1)
	v_mov_b32_e32 v198, v192
	v_mov_b32_e32 v199, v193
	v_sub_f32_e32 v125, v207, v102
	ds_read2_b64 v[204:207], v0 offset0:92 offset1:96
	v_exp_f32_e32 v123, v123
	v_exp_f32_e32 v125, v125
	s_waitcnt lgkmcnt(1)
	v_mfma_f32_16x16x32_bf16 v[180:183], v[200:203], v[188:191], v[180:183]
	ds_read2_b64 v[200:203], v100 offset0:24 offset1:28
	v_add_f32_e32 v103, v121, v103
	v_add_f32_e32 v103, v123, v103
	v_mfma_f32_16x16x32_bf16 v[176:179], v[196:199], v[188:191], v[176:179]
	v_mov_b32_e32 v196, v222
	v_mov_b32_e32 v197, v223
	s_waitcnt lgkmcnt(1)
	v_mov_b32_e32 v198, v204
	v_mov_b32_e32 v199, v205
	v_add_f32_e32 v100, v125, v103
	ds_bpermute_b32 v103, v141, v100
	v_mfma_f32_16x16x32_bf16 v[170:173], v[196:199], v[188:191], v[170:173]
	v_cvt_pk_bf16_f32 v188, v231, v232
	v_cvt_pk_bf16_f32 v189, v233, v234
	v_cvt_pk_bf16_f32 v190, v235, v236
	ds_read2_b64 v[196:199], v1 offset0:36 offset1:40
	v_cvt_pk_bf16_f32 v191, v237, v238
	ds_read2_b64 v[220:223], v0 offset0:100 offset1:104
	s_waitcnt lgkmcnt(2)
	v_add_f32_e32 v100, v100, v103
	v_mfma_f32_16x16x32_bf16 v[130:133], v[200:203], v[188:191], v[130:133]
	ds_read2_b64 v[200:203], v3 offset0:88 offset1:92
	ds_bpermute_b32 v103, v142, v100
	v_fma_f32 v101, v101, s65, -v102
	v_mov_b32_e32 v192, v194
	v_mov_b32_e32 v193, v195
	s_waitcnt lgkmcnt(3)
	v_mov_b32_e32 v194, v196
	v_mov_b32_e32 v195, v197
	v_cvt_pk_bf16_f32 v0, v239, v121
	v_mov_b32_e32 v204, v206
	v_mov_b32_e32 v205, v207
	s_waitcnt lgkmcnt(2)
	v_mov_b32_e32 v206, v220
	v_mov_b32_e32 v207, v221
	v_exp_f32_e32 v121, v101
	v_cvt_pk_bf16_f32 v1, v123, v125
	s_waitcnt lgkmcnt(0)
	v_add_f32_e32 v123, v100, v103
	v_mfma_f32_16x16x32_bf16 v[192:195], v[192:195], v[188:191], v[176:179]
	v_add_f32_e32 v121, v121, v123
	v_mov_b32_e32 v196, v198
	v_mov_b32_e32 v197, v199
	v_mfma_f32_16x16x32_bf16 v[178:181], v[200:203], v[188:191], v[180:183]
	v_mov_b32_e32 v176, v174
	v_mov_b32_e32 v177, v175
	v_mov_b32_e32 v220, v222
	v_mfma_f32_16x16x32_bf16 v[170:173], v[204:207], v[188:191], v[170:173]
	v_mov_b32_e32 v188, v186
	v_mov_b32_e32 v189, v187
	v_mov_b32_e32 v221, v223
	v_div_scale_f32 v123, s[40:41], v121, v121, 1.0
	v_rcp_f32_e32 v125, v123
	v_mov_b32_e32 v3, v2
	v_lshl_add_u64 v[96:97], v[96:97], 0, v[98:99]
	v_lshl_add_u64 v[134:135], s[72:73], 0, v[96:97]
	v_mfma_f32_16x16x32_bf16 v[130:133], v[174:177], v[0:3], v[130:133]
	s_or_b32 s42, s14, 1
	s_cmp_lg_u32 s14, 2
	v_mfma_f32_16x16x32_bf16 v[174:177], v[196:199], v[0:3], v[192:195]
	v_mfma_f32_16x16x32_bf16 v[100:103], v[186:189], v[0:3], v[178:181]
	v_mfma_f32_16x16x32_bf16 v[170:173], v[220:223], v[0:3], v[170:173]
	v_fma_f32 v0, -v123, v125, 1.0
	v_fmac_f32_e32 v125, v0, v125
	v_div_scale_f32 v0, vcc, 1.0, v121, 1.0
	v_mul_f32_e32 v1, v0, v125
	v_fma_f32 v3, -v123, v1, v0
	v_fmac_f32_e32 v1, v3, v125
	v_fma_f32 v0, -v123, v1, v0
	v_div_fmas_f32 v0, v0, v125, v1
	v_div_fixup_f32 v0, v0, v121, 1.0
	v_pk_mul_f32 v[96:97], v[130:131], v[0:1] op_sel_hi:[1,0]
	v_pk_mul_f32 v[98:99], v[132:133], v[0:1] op_sel_hi:[1,0]
	v_cvt_pk_bf16_f32 v96, v96, v97
	v_cvt_pk_bf16_f32 v97, v98, v99
	v_pk_mul_f32 v[98:99], v[174:175], v[0:1] op_sel_hi:[1,0]
	v_pk_mul_f32 v[130:131], v[176:177], v[0:1] op_sel_hi:[1,0]
	v_cvt_pk_bf16_f32 v98, v98, v99
	v_cvt_pk_bf16_f32 v99, v130, v131
	v_add_co_u32_e32 v130, vcc, s74, v134
	v_mov_b32_e32 v3, v113
	s_nop 0
	v_addc_co_u32_e32 v131, vcc, 0, v135, vcc
	global_store_dwordx4 v[130:131], v[96:99], off offset:1024 nt
	s_nop 1
	v_pk_mul_f32 v[96:97], v[100:101], v[0:1] op_sel_hi:[1,0]
	v_pk_mul_f32 v[98:99], v[102:103], v[0:1] op_sel_hi:[1,0]
	v_cvt_pk_bf16_f32 v96, v96, v97
	v_cvt_pk_bf16_f32 v97, v98, v99
	v_pk_mul_f32 v[98:99], v[170:171], v[0:1] op_sel_hi:[1,0]
	v_pk_mul_f32 v[0:1], v[172:173], v[0:1] op_sel_hi:[1,0]
	v_cvt_pk_bf16_f32 v98, v98, v99
	v_cvt_pk_bf16_f32 v99, v0, v1
	v_mov_b32_e32 v0, v112
	global_store_dwordx4 v[130:131], v[96:99], off offset:1088 nt
	s_nop 0
	v_ashrrev_i32_e32 v1, 31, v0
	v_lshlrev_b32_e32 v130, 3, v3
	v_ashrrev_i32_e32 v131, 31, v130
	v_lshl_add_u64 v[132:133], v[126:127], 0, v[0:1]
	s_cbranch_scc0 .LBB0_431
	s_or_b32 s40, s42, s15
	v_lshlrev_b64 v[96:97], 1, v[130:131]
	s_lshl_b32 s94, s40, 6
	v_mad_u64_u32 v[96:97], s[40:41], v132, s62, v[96:97]
	v_mov_b32_e32 v98, v97
	v_mad_u64_u32 v[98:99], s[40:41], v133, s62, v[98:99]
	s_add_u32 s40, s12, s70
	v_mov_b32_e32 v97, v98
	s_addc_u32 s41, s13, s71
	v_lshl_add_u64 v[96:97], s[40:41], 0, v[96:97]
	v_add_co_u32_e32 v100, vcc, 0xbe00000, v96
	s_nop 1
	v_addc_co_u32_e32 v101, vcc, 0, v97, vcc
	global_load_dwordx4 v[96:99], v[100:101], off offset:3328
	s_nop 0
	global_load_dwordx4 v[100:103], v[100:101], off offset:3392
	v_mov_b64_e32 v[134:135], s[94:95]
	s_mov_b32 s57, 0x42fc0000
	s_cbranch_execnz .LBB0_428
	s_branch .LBB0_427
